# MLP1A and MLP1B tiles rewritten by hand with v_mfma_f32_16x16x32_f16 (same fp16 operands, fp32 accumulate), pipelined K loop, relu^2 epilogue in the 16x16 layout
# speedup vs baseline: 1.0089x; 1.0089x over previous
.LBB0_107:
	s_and_b64 vcc, exec, s[42:43]
	s_cbranch_vccz .LBB0_127
	v_readlane_b32 s24, v236, 10
	v_readlane_b32 s25, v236, 11
	s_andn2_b64 vcc, exec, s[24:25]
	s_cbranch_vccnz .LBB0_127
	s_load_dwordx2 s[24:25], s[22:23], 0x110
	s_load_dwordx2 s[28:29], s[22:23], 0x70
	v_readlane_b32 s56, v236, 21
	s_waitcnt lgkmcnt(0)
	s_add_u32 s42, s24, 0x8208000
	s_addc_u32 s43, s25, 0
	s_add_u32 s44, s24, 0xd00000
	s_addc_u32 s45, s25, 0
	s_add_u32 s54, s28, 0x4000
	s_addc_u32 s55, s29, 0
	s_add_u32 s46, s24, 0xaa08000
	s_addc_u32 s47, s25, 0
	s_add_u32 s48, s24, 0xd000c0
	s_addc_u32 s49, s25, 0
	s_add_u32 s50, s24, 0x82080c0
	s_addc_u32 s51, s25, 0
	s_branch .LBB0_111
.LBB0_111:
	s_ashr_i32 s24, s56, 31
	s_lshr_b32 s24, s24, 28
	s_add_i32 s24, s56, s24
	s_ashr_i32 s25, s24, 4
	s_lshl_b32 s24, s25, 3
	s_or_b32 s24, s24, s83
	s_and_b64 s[28:29], s[74:75], exec
	s_cselect_b32 s24, s24, s25
	s_lshl_b32 s36, s24, 8
	s_cmp_gt_i32 s24, 39
	s_mov_b64 s[30:31], -1
	s_cbranch_scc0 .LBB0_113
	s_add_i32 s90, s36, 0xffffd800
	s_mov_b64 s[30:31], 0
	s_mov_b64 s[28:29], s[90:91]

.LBB0_115:
	s_lshl_b32 s65, s25, 4
	s_sub_i32 s65, s56, s65
	s_lshl_b32 s65, s65, 8
	s_lshl_b32 vcc_hi, s36, 11
	s_add_u32 s30, s42, vcc_hi
	s_addc_u32 s31, s43, 0
	s_lshl_b32 vcc_hi, s65, 11
	s_add_u32 s52, s44, vcc_hi
	s_addc_u32 s53, s45, 0
	s_waitcnt lgkmcnt(0)
	v_readfirstlane_b32 vcc_hi, v200
	s_lshr_b32 vcc_hi, vcc_hi, 6
	s_lshl_b32 s24, vcc_hi, 11
	s_add_u32 s24, s24, 16
	s_lshl_b32 vcc_hi, vcc_hi, 16
	s_add_u32 s30, s30, vcc_hi
	s_addc_u32 s31, s31, 0
	s_add_u32 s52, s52, vcc_hi
	s_addc_u32 s53, s53, 0
	v_bfe_u32 v173, v200, 4, 2
	v_sub_u32_e32 v173, 0, v173
	v_and_b32_e32 v173, 3, v173
	v_and_b32_e32 v172, 3, v200
	v_xor_b32_e32 v172, v172, v173
	v_bfe_u32 v173, v200, 2, 4
	v_lshlrev_b32_e32 v173, 11, v173
	v_lshl_or_b32 v170, v172, 4, v173
	v_add_u32_e32 v171, 0x8000, v170
	v_bfe_u32 v172, v200, 2, 2
	v_sub_u32_e32 v172, 0, v172
	v_and_b32_e32 v172, 3, v172
	v_bfe_u32 v173, v200, 4, 2
	v_xor_b32_e32 v172, v172, v173
	v_and_b32_e32 v173, 15, v200
	v_bfe_u32 v174, v200, 8, 1
	v_lshl_or_b32 v174, v174, 7, v173
	v_lshlrev_b32_e32 v174, 6, v174
	v_lshl_or_b32 v164, v172, 4, v174
	v_bfe_u32 v174, v200, 6, 2
	v_lshl_or_b32 v174, v174, 6, v173
	v_lshlrev_b32_e32 v174, 6, v174
	v_lshl_or_b32 v165, v172, 4, v174
	v_add_u32_e32 v165, 0x4000, v165
	v_bfe_u32 v172, v200, 6, 2
	v_bfe_u32 v173, v200, 4, 2
	v_lshlrev_b32_e32 v172, 6, v172
	v_lshl_or_b32 v172, v173, 2, v172
	v_add_u32_e32 v172, s65, v172
	v_lshlrev_b32_e32 v172, 2, v172
	global_load_dwordx4 v[132:135], v172, s[54:55]
	global_load_dwordx4 v[136:139], v172, s[54:55] offset:64
	global_load_dwordx4 v[140:143], v172, s[54:55] offset:128
	global_load_dwordx4 v[144:147], v172, s[54:55] offset:192
	s_mov_b32 s37, s24
	s_mov_b32 m0, s37
	s_nop 0
	global_load_lds_dwordx4 v170, s[30:31]
	s_add_u32 m0, s37, 0x400
	s_nop 0
	global_load_lds_dwordx4 v171, s[30:31]
	s_add_u32 m0, s37, 0x4000
	s_nop 0
	global_load_lds_dwordx4 v170, s[52:53]
	s_add_u32 m0, s37, 0x4400
	s_nop 0
	global_load_lds_dwordx4 v171, s[52:53]
	s_add_u32 s30, s30, 64
	s_addc_u32 s31, s31, 0
	s_add_u32 s52, s52, 64
	s_addc_u32 s53, s53, 0
	s_add_u32 s37, s24, 0x8000
	s_mov_b32 m0, s37
	s_nop 0
	global_load_lds_dwordx4 v170, s[30:31]
	s_add_u32 m0, s37, 0x400
	s_nop 0
	global_load_lds_dwordx4 v171, s[30:31]
	s_add_u32 m0, s37, 0x4000
	s_nop 0
	global_load_lds_dwordx4 v170, s[52:53]
	s_add_u32 m0, s37, 0x4400
	s_nop 0
	global_load_lds_dwordx4 v171, s[52:53]
	s_add_u32 s30, s30, 64
	s_addc_u32 s31, s31, 0
	s_add_u32 s52, s52, 64
	s_addc_u32 s53, s53, 0
	s_add_u32 s37, s24, 0x10000
	s_mov_b32 m0, s37
	s_nop 0
	global_load_lds_dwordx4 v170, s[30:31]
	s_add_u32 m0, s37, 0x400
	s_nop 0
	global_load_lds_dwordx4 v171, s[30:31]
	s_add_u32 m0, s37, 0x4000
	s_nop 0
	global_load_lds_dwordx4 v170, s[52:53]
	s_add_u32 m0, s37, 0x4400
	s_nop 0
	global_load_lds_dwordx4 v171, s[52:53]
	s_add_u32 s30, s30, 64
	s_addc_u32 s31, s31, 0
	s_add_u32 s52, s52, 64
	s_addc_u32 s53, s53, 0
	s_add_u32 s37, s24, 0x18000
	s_mov_b32 m0, s37
	s_nop 0
	global_load_lds_dwordx4 v170, s[30:31]
	s_add_u32 m0, s37, 0x400
	s_nop 0
	global_load_lds_dwordx4 v171, s[30:31]
	s_add_u32 m0, s37, 0x4000
	s_nop 0
	global_load_lds_dwordx4 v170, s[52:53]
	s_add_u32 m0, s37, 0x4400
	s_nop 0
	global_load_lds_dwordx4 v171, s[52:53]
	s_add_u32 s30, s30, 64
	s_addc_u32 s31, s31, 0
	s_add_u32 s52, s52, 64
	s_addc_u32 s53, s53, 0
	s_waitcnt vmcnt(12)
	s_barrier
	v_mov_b32_e32 v4, v132
	v_mov_b32_e32 v5, v133
	v_mov_b32_e32 v6, v134
	v_mov_b32_e32 v7, v135
	v_mov_b32_e32 v8, v136
	v_mov_b32_e32 v9, v137
	v_mov_b32_e32 v10, v138
	v_mov_b32_e32 v11, v139
	v_mov_b32_e32 v12, v140
	v_mov_b32_e32 v13, v141
	v_mov_b32_e32 v14, v142
	v_mov_b32_e32 v15, v143
	v_mov_b32_e32 v16, v144
	v_mov_b32_e32 v17, v145
	v_mov_b32_e32 v18, v146
	v_mov_b32_e32 v19, v147
	v_mov_b32_e32 v20, v132
	v_mov_b32_e32 v21, v133
	v_mov_b32_e32 v22, v134
	v_mov_b32_e32 v23, v135
	v_mov_b32_e32 v24, v136
	v_mov_b32_e32 v25, v137
	v_mov_b32_e32 v26, v138
	v_mov_b32_e32 v27, v139
	v_mov_b32_e32 v28, v140
	v_mov_b32_e32 v29, v141
	v_mov_b32_e32 v30, v142
	v_mov_b32_e32 v31, v143
	v_mov_b32_e32 v32, v144
	v_mov_b32_e32 v33, v145
	v_mov_b32_e32 v34, v146
	v_mov_b32_e32 v35, v147
	v_mov_b32_e32 v36, v132
	v_mov_b32_e32 v37, v133
	v_mov_b32_e32 v38, v134
	v_mov_b32_e32 v39, v135
	v_mov_b32_e32 v40, v136
	v_mov_b32_e32 v41, v137
	v_mov_b32_e32 v42, v138
	v_mov_b32_e32 v43, v139
	v_mov_b32_e32 v44, v140
	v_mov_b32_e32 v45, v141
	v_mov_b32_e32 v46, v142
	v_mov_b32_e32 v47, v143
	v_mov_b32_e32 v48, v144
	v_mov_b32_e32 v49, v145
	v_mov_b32_e32 v50, v146
	v_mov_b32_e32 v51, v147
	v_mov_b32_e32 v52, v132
	v_mov_b32_e32 v53, v133
	v_mov_b32_e32 v54, v134
	v_mov_b32_e32 v55, v135
	v_mov_b32_e32 v56, v136
	v_mov_b32_e32 v57, v137
	v_mov_b32_e32 v58, v138
	v_mov_b32_e32 v59, v139
	v_mov_b32_e32 v60, v140
	v_mov_b32_e32 v61, v141
	v_mov_b32_e32 v62, v142
	v_mov_b32_e32 v63, v143
	v_mov_b32_e32 v64, v144
	v_mov_b32_e32 v65, v145
	v_mov_b32_e32 v66, v146
	v_mov_b32_e32 v67, v147
	v_mov_b32_e32 v68, v132
	v_mov_b32_e32 v69, v133
	v_mov_b32_e32 v70, v134
	v_mov_b32_e32 v71, v135
	v_mov_b32_e32 v72, v136
	v_mov_b32_e32 v73, v137
	v_mov_b32_e32 v74, v138
	v_mov_b32_e32 v75, v139
	v_mov_b32_e32 v76, v140
	v_mov_b32_e32 v77, v141
	v_mov_b32_e32 v78, v142
	v_mov_b32_e32 v79, v143
	v_mov_b32_e32 v80, v144
	v_mov_b32_e32 v81, v145
	v_mov_b32_e32 v82, v146
	v_mov_b32_e32 v83, v147
	v_mov_b32_e32 v84, v132
	v_mov_b32_e32 v85, v133
	v_mov_b32_e32 v86, v134
	v_mov_b32_e32 v87, v135
	v_mov_b32_e32 v88, v136
	v_mov_b32_e32 v89, v137
	v_mov_b32_e32 v90, v138
	v_mov_b32_e32 v91, v139
	v_mov_b32_e32 v92, v140
	v_mov_b32_e32 v93, v141
	v_mov_b32_e32 v94, v142
	v_mov_b32_e32 v95, v143
	v_mov_b32_e32 v96, v144
	v_mov_b32_e32 v97, v145
	v_mov_b32_e32 v98, v146
	v_mov_b32_e32 v99, v147
	v_mov_b32_e32 v100, v132
	v_mov_b32_e32 v101, v133
	v_mov_b32_e32 v102, v134
	v_mov_b32_e32 v103, v135
	v_mov_b32_e32 v104, v136
	v_mov_b32_e32 v105, v137
	v_mov_b32_e32 v106, v138
	v_mov_b32_e32 v107, v139
	v_mov_b32_e32 v108, v140
	v_mov_b32_e32 v109, v141
	v_mov_b32_e32 v110, v142
	v_mov_b32_e32 v111, v143
	v_mov_b32_e32 v112, v144
	v_mov_b32_e32 v113, v145
	v_mov_b32_e32 v114, v146
	v_mov_b32_e32 v115, v147
	v_mov_b32_e32 v116, v132
	v_mov_b32_e32 v117, v133
	v_mov_b32_e32 v118, v134
	v_mov_b32_e32 v119, v135
	v_mov_b32_e32 v120, v136
	v_mov_b32_e32 v121, v137
	v_mov_b32_e32 v122, v138
	v_mov_b32_e32 v123, v139
	v_mov_b32_e32 v124, v140
	v_mov_b32_e32 v125, v141
	v_mov_b32_e32 v126, v142
	v_mov_b32_e32 v127, v143
	v_mov_b32_e32 v128, v144
	v_mov_b32_e32 v129, v145
	v_mov_b32_e32 v130, v146
	v_mov_b32_e32 v131, v147
	s_mov_b32 s32, 0
	s_mov_b32 s57, 0
	s_nop 1
	v_add_u32_e32 v168, s32, v165
	v_add_u32_e32 v169, s32, v164
	ds_read_b128 v[132:135], v168 offset:16
	ds_read_b128 v[136:139], v168 offset:1040
	ds_read_b128 v[140:143], v168 offset:2064
	ds_read_b128 v[144:147], v168 offset:3088
	ds_read_b128 v[184:187], v169 offset:16
	ds_read_b128 v[188:191], v169 offset:1040
	ds_read_b128 v[192:195], v169 offset:2064
	ds_read_b128 v[196:199], v169 offset:3088
	s_waitcnt lgkmcnt(0)
.Lt_mlp1b:
	v_add_u32_e32 v169, s32, v164
	v_mfma_f32_16x16x32_f16 v[4:7], v[132:135], v[184:187], v[4:7]
	ds_read_b128 v[238:241], v169 offset:4112
	v_mfma_f32_16x16x32_f16 v[8:11], v[136:139], v[184:187], v[8:11]
	ds_read_b128 v[242:245], v169 offset:5136
	v_mfma_f32_16x16x32_f16 v[12:15], v[140:143], v[184:187], v[12:15]
	ds_read_b128 v[246:249], v169 offset:6160
	v_mfma_f32_16x16x32_f16 v[16:19], v[144:147], v[184:187], v[16:19]
	ds_read_b128 v[250:253], v169 offset:7184
	v_mfma_f32_16x16x32_f16 v[20:23], v[132:135], v[188:191], v[20:23]
	v_mfma_f32_16x16x32_f16 v[24:27], v[136:139], v[188:191], v[24:27]
	v_mfma_f32_16x16x32_f16 v[28:31], v[140:143], v[188:191], v[28:31]
	v_mfma_f32_16x16x32_f16 v[32:35], v[144:147], v[188:191], v[32:35]
	v_mfma_f32_16x16x32_f16 v[36:39], v[132:135], v[192:195], v[36:39]
	v_mfma_f32_16x16x32_f16 v[40:43], v[136:139], v[192:195], v[40:43]
	v_mfma_f32_16x16x32_f16 v[44:47], v[140:143], v[192:195], v[44:47]
	v_mfma_f32_16x16x32_f16 v[48:51], v[144:147], v[192:195], v[48:51]
	v_mfma_f32_16x16x32_f16 v[52:55], v[132:135], v[196:199], v[52:55]
	v_mfma_f32_16x16x32_f16 v[56:59], v[136:139], v[196:199], v[56:59]
	v_mfma_f32_16x16x32_f16 v[60:63], v[140:143], v[196:199], v[60:63]
	v_mfma_f32_16x16x32_f16 v[64:67], v[144:147], v[196:199], v[64:67]
	s_waitcnt vmcnt(8) lgkmcnt(0)
	s_barrier
	s_add_i32 s37, s32, 0x8000
	s_cmp_lg_u32 s32, 0x18000
	s_cselect_b32 s37, s37, 0
	v_add_u32_e32 v168, s37, v165
	v_add_u32_e32 v169, s37, v164
	s_add_u32 vcc_lo, s24, s32
	v_mfma_f32_16x16x32_f16 v[68:71], v[132:135], v[238:241], v[68:71]
	ds_read_b128 v[148:151], v168 offset:16
	ds_read_b128 v[184:187], v169 offset:16
	v_mfma_f32_16x16x32_f16 v[72:75], v[136:139], v[238:241], v[72:75]
	ds_read_b128 v[152:155], v168 offset:1040
	ds_read_b128 v[188:191], v169 offset:1040
	v_mfma_f32_16x16x32_f16 v[76:79], v[140:143], v[238:241], v[76:79]
	ds_read_b128 v[156:159], v168 offset:2064
	ds_read_b128 v[192:195], v169 offset:2064
	v_mfma_f32_16x16x32_f16 v[80:83], v[144:147], v[238:241], v[80:83]
	ds_read_b128 v[160:163], v168 offset:3088
	ds_read_b128 v[196:199], v169 offset:3088
	v_mfma_f32_16x16x32_f16 v[84:87], v[132:135], v[242:245], v[84:87]
	v_mfma_f32_16x16x32_f16 v[88:91], v[136:139], v[242:245], v[88:91]
	v_mfma_f32_16x16x32_f16 v[92:95], v[140:143], v[242:245], v[92:95]
	v_mfma_f32_16x16x32_f16 v[96:99], v[144:147], v[242:245], v[96:99]
	v_mfma_f32_16x16x32_f16 v[100:103], v[132:135], v[246:249], v[100:103]
	s_mov_b32 m0, vcc_lo
	s_nop 0
	global_load_lds_dwordx4 v170, s[30:31]
	v_mfma_f32_16x16x32_f16 v[104:107], v[136:139], v[246:249], v[104:107]
	s_add_u32 m0, vcc_lo, 0x400
	s_nop 0
	global_load_lds_dwordx4 v171, s[30:31]
	v_mfma_f32_16x16x32_f16 v[108:111], v[140:143], v[246:249], v[108:111]
	s_add_u32 m0, vcc_lo, 0x4000
	s_nop 0
	global_load_lds_dwordx4 v170, s[52:53]
	v_mfma_f32_16x16x32_f16 v[112:115], v[144:147], v[246:249], v[112:115]
	s_add_u32 m0, vcc_lo, 0x4400
	s_nop 0
	global_load_lds_dwordx4 v171, s[52:53]
	v_mfma_f32_16x16x32_f16 v[116:119], v[132:135], v[250:253], v[116:119]
	v_mfma_f32_16x16x32_f16 v[120:123], v[136:139], v[250:253], v[120:123]
	v_mfma_f32_16x16x32_f16 v[124:127], v[140:143], v[250:253], v[124:127]
	v_mfma_f32_16x16x32_f16 v[128:131], v[144:147], v[250:253], v[128:131]
	s_waitcnt lgkmcnt(0)
	s_mov_b32 s32, s37
	s_add_u32 s30, s30, 64
	s_addc_u32 s31, s31, 0
	s_add_u32 s52, s52, 64
	s_addc_u32 s53, s53, 0
	v_add_u32_e32 v169, s32, v164
	v_mfma_f32_16x16x32_f16 v[4:7], v[148:151], v[184:187], v[4:7]
	ds_read_b128 v[238:241], v169 offset:4112
	v_mfma_f32_16x16x32_f16 v[8:11], v[152:155], v[184:187], v[8:11]
	ds_read_b128 v[242:245], v169 offset:5136
	v_mfma_f32_16x16x32_f16 v[12:15], v[156:159], v[184:187], v[12:15]
	ds_read_b128 v[246:249], v169 offset:6160
	v_mfma_f32_16x16x32_f16 v[16:19], v[160:163], v[184:187], v[16:19]
	ds_read_b128 v[250:253], v169 offset:7184
	v_mfma_f32_16x16x32_f16 v[20:23], v[148:151], v[188:191], v[20:23]
	v_mfma_f32_16x16x32_f16 v[24:27], v[152:155], v[188:191], v[24:27]
	v_mfma_f32_16x16x32_f16 v[28:31], v[156:159], v[188:191], v[28:31]
	v_mfma_f32_16x16x32_f16 v[32:35], v[160:163], v[188:191], v[32:35]
	v_mfma_f32_16x16x32_f16 v[36:39], v[148:151], v[192:195], v[36:39]
	v_mfma_f32_16x16x32_f16 v[40:43], v[152:155], v[192:195], v[40:43]
	v_mfma_f32_16x16x32_f16 v[44:47], v[156:159], v[192:195], v[44:47]
	v_mfma_f32_16x16x32_f16 v[48:51], v[160:163], v[192:195], v[48:51]
	v_mfma_f32_16x16x32_f16 v[52:55], v[148:151], v[196:199], v[52:55]
	v_mfma_f32_16x16x32_f16 v[56:59], v[152:155], v[196:199], v[56:59]
	v_mfma_f32_16x16x32_f16 v[60:63], v[156:159], v[196:199], v[60:63]
	v_mfma_f32_16x16x32_f16 v[64:67], v[160:163], v[196:199], v[64:67]
	s_waitcnt vmcnt(8) lgkmcnt(0)
	s_barrier
	s_add_i32 s37, s32, 0x8000
	s_cmp_lg_u32 s32, 0x18000
	s_cselect_b32 s37, s37, 0
	v_add_u32_e32 v168, s37, v165
	v_add_u32_e32 v169, s37, v164
	s_add_u32 vcc_lo, s24, s32
	v_mfma_f32_16x16x32_f16 v[68:71], v[148:151], v[238:241], v[68:71]
	ds_read_b128 v[132:135], v168 offset:16
	ds_read_b128 v[184:187], v169 offset:16
	v_mfma_f32_16x16x32_f16 v[72:75], v[152:155], v[238:241], v[72:75]
	ds_read_b128 v[136:139], v168 offset:1040
	ds_read_b128 v[188:191], v169 offset:1040
	v_mfma_f32_16x16x32_f16 v[76:79], v[156:159], v[238:241], v[76:79]
	ds_read_b128 v[140:143], v168 offset:2064
	ds_read_b128 v[192:195], v169 offset:2064
	v_mfma_f32_16x16x32_f16 v[80:83], v[160:163], v[238:241], v[80:83]
	ds_read_b128 v[144:147], v168 offset:3088
	ds_read_b128 v[196:199], v169 offset:3088
	v_mfma_f32_16x16x32_f16 v[84:87], v[148:151], v[242:245], v[84:87]
	v_mfma_f32_16x16x32_f16 v[88:91], v[152:155], v[242:245], v[88:91]
	v_mfma_f32_16x16x32_f16 v[92:95], v[156:159], v[242:245], v[92:95]
	v_mfma_f32_16x16x32_f16 v[96:99], v[160:163], v[242:245], v[96:99]
	v_mfma_f32_16x16x32_f16 v[100:103], v[148:151], v[246:249], v[100:103]
	s_mov_b32 m0, vcc_lo
	s_nop 0
	global_load_lds_dwordx4 v170, s[30:31]
	v_mfma_f32_16x16x32_f16 v[104:107], v[152:155], v[246:249], v[104:107]
	s_add_u32 m0, vcc_lo, 0x400
	s_nop 0
	global_load_lds_dwordx4 v171, s[30:31]
	v_mfma_f32_16x16x32_f16 v[108:111], v[156:159], v[246:249], v[108:111]
	s_add_u32 m0, vcc_lo, 0x4000
	s_nop 0
	global_load_lds_dwordx4 v170, s[52:53]
	v_mfma_f32_16x16x32_f16 v[112:115], v[160:163], v[246:249], v[112:115]
	s_add_u32 m0, vcc_lo, 0x4400
	s_nop 0
	global_load_lds_dwordx4 v171, s[52:53]
	v_mfma_f32_16x16x32_f16 v[116:119], v[148:151], v[250:253], v[116:119]
	v_mfma_f32_16x16x32_f16 v[120:123], v[152:155], v[250:253], v[120:123]
	v_mfma_f32_16x16x32_f16 v[124:127], v[156:159], v[250:253], v[124:127]
	v_mfma_f32_16x16x32_f16 v[128:131], v[160:163], v[250:253], v[128:131]
	s_waitcnt lgkmcnt(0)
	s_mov_b32 s32, s37
	s_add_u32 s30, s30, 64
	s_addc_u32 s31, s31, 0
	s_add_u32 s52, s52, 64
	s_addc_u32 s53, s53, 0
	s_add_i32 s57, s57, 2
	s_cmp_lt_u32 s57, 28
	s_cbranch_scc1 .Lt_mlp1b
	v_add_u32_e32 v169, s32, v164
	v_mfma_f32_16x16x32_f16 v[4:7], v[132:135], v[184:187], v[4:7]
	ds_read_b128 v[238:241], v169 offset:4112
	v_mfma_f32_16x16x32_f16 v[8:11], v[136:139], v[184:187], v[8:11]
	ds_read_b128 v[242:245], v169 offset:5136
	v_mfma_f32_16x16x32_f16 v[12:15], v[140:143], v[184:187], v[12:15]
	ds_read_b128 v[246:249], v169 offset:6160
	v_mfma_f32_16x16x32_f16 v[16:19], v[144:147], v[184:187], v[16:19]
	ds_read_b128 v[250:253], v169 offset:7184
	v_mfma_f32_16x16x32_f16 v[20:23], v[132:135], v[188:191], v[20:23]
	v_mfma_f32_16x16x32_f16 v[24:27], v[136:139], v[188:191], v[24:27]
	v_mfma_f32_16x16x32_f16 v[28:31], v[140:143], v[188:191], v[28:31]
	v_mfma_f32_16x16x32_f16 v[32:35], v[144:147], v[188:191], v[32:35]
	v_mfma_f32_16x16x32_f16 v[36:39], v[132:135], v[192:195], v[36:39]
	v_mfma_f32_16x16x32_f16 v[40:43], v[136:139], v[192:195], v[40:43]
	v_mfma_f32_16x16x32_f16 v[44:47], v[140:143], v[192:195], v[44:47]
	v_mfma_f32_16x16x32_f16 v[48:51], v[144:147], v[192:195], v[48:51]
	v_mfma_f32_16x16x32_f16 v[52:55], v[132:135], v[196:199], v[52:55]
	v_mfma_f32_16x16x32_f16 v[56:59], v[136:139], v[196:199], v[56:59]
	v_mfma_f32_16x16x32_f16 v[60:63], v[140:143], v[196:199], v[60:63]
	v_mfma_f32_16x16x32_f16 v[64:67], v[144:147], v[196:199], v[64:67]
	s_waitcnt vmcnt(8) lgkmcnt(0)
	s_barrier
	s_add_i32 s37, s32, 0x8000
	s_cmp_lg_u32 s32, 0x18000
	s_cselect_b32 s37, s37, 0
	v_add_u32_e32 v168, s37, v165
	v_add_u32_e32 v169, s37, v164
	v_mfma_f32_16x16x32_f16 v[68:71], v[132:135], v[238:241], v[68:71]
	ds_read_b128 v[148:151], v168 offset:16
	ds_read_b128 v[184:187], v169 offset:16
	v_mfma_f32_16x16x32_f16 v[72:75], v[136:139], v[238:241], v[72:75]
	ds_read_b128 v[152:155], v168 offset:1040
	ds_read_b128 v[188:191], v169 offset:1040
	v_mfma_f32_16x16x32_f16 v[76:79], v[140:143], v[238:241], v[76:79]
	ds_read_b128 v[156:159], v168 offset:2064
	ds_read_b128 v[192:195], v169 offset:2064
	v_mfma_f32_16x16x32_f16 v[80:83], v[144:147], v[238:241], v[80:83]
	ds_read_b128 v[160:163], v168 offset:3088
	ds_read_b128 v[196:199], v169 offset:3088
	v_mfma_f32_16x16x32_f16 v[84:87], v[132:135], v[242:245], v[84:87]
	v_mfma_f32_16x16x32_f16 v[88:91], v[136:139], v[242:245], v[88:91]
	v_mfma_f32_16x16x32_f16 v[92:95], v[140:143], v[242:245], v[92:95]
	v_mfma_f32_16x16x32_f16 v[96:99], v[144:147], v[242:245], v[96:99]
	v_mfma_f32_16x16x32_f16 v[100:103], v[132:135], v[246:249], v[100:103]
	v_mfma_f32_16x16x32_f16 v[104:107], v[136:139], v[246:249], v[104:107]
	v_mfma_f32_16x16x32_f16 v[108:111], v[140:143], v[246:249], v[108:111]
	v_mfma_f32_16x16x32_f16 v[112:115], v[144:147], v[246:249], v[112:115]
	v_mfma_f32_16x16x32_f16 v[116:119], v[132:135], v[250:253], v[116:119]
	v_mfma_f32_16x16x32_f16 v[120:123], v[136:139], v[250:253], v[120:123]
	v_mfma_f32_16x16x32_f16 v[124:127], v[140:143], v[250:253], v[124:127]
	v_mfma_f32_16x16x32_f16 v[128:131], v[144:147], v[250:253], v[128:131]
	s_waitcnt lgkmcnt(0)
	s_mov_b32 s32, s37
	v_add_u32_e32 v169, s32, v164
	v_mfma_f32_16x16x32_f16 v[4:7], v[148:151], v[184:187], v[4:7]
	ds_read_b128 v[238:241], v169 offset:4112
	v_mfma_f32_16x16x32_f16 v[8:11], v[152:155], v[184:187], v[8:11]
	ds_read_b128 v[242:245], v169 offset:5136
	v_mfma_f32_16x16x32_f16 v[12:15], v[156:159], v[184:187], v[12:15]
	ds_read_b128 v[246:249], v169 offset:6160
	v_mfma_f32_16x16x32_f16 v[16:19], v[160:163], v[184:187], v[16:19]
	ds_read_b128 v[250:253], v169 offset:7184
	v_mfma_f32_16x16x32_f16 v[20:23], v[148:151], v[188:191], v[20:23]
	v_mfma_f32_16x16x32_f16 v[24:27], v[152:155], v[188:191], v[24:27]
	v_mfma_f32_16x16x32_f16 v[28:31], v[156:159], v[188:191], v[28:31]
	v_mfma_f32_16x16x32_f16 v[32:35], v[160:163], v[188:191], v[32:35]
	v_mfma_f32_16x16x32_f16 v[36:39], v[148:151], v[192:195], v[36:39]
	v_mfma_f32_16x16x32_f16 v[40:43], v[152:155], v[192:195], v[40:43]
	v_mfma_f32_16x16x32_f16 v[44:47], v[156:159], v[192:195], v[44:47]
	v_mfma_f32_16x16x32_f16 v[48:51], v[160:163], v[192:195], v[48:51]
	v_mfma_f32_16x16x32_f16 v[52:55], v[148:151], v[196:199], v[52:55]
	v_mfma_f32_16x16x32_f16 v[56:59], v[152:155], v[196:199], v[56:59]
	v_mfma_f32_16x16x32_f16 v[60:63], v[156:159], v[196:199], v[60:63]
	v_mfma_f32_16x16x32_f16 v[64:67], v[160:163], v[196:199], v[64:67]
	s_waitcnt vmcnt(4) lgkmcnt(0)
	s_barrier
	s_add_i32 s37, s32, 0x8000
	s_cmp_lg_u32 s32, 0x18000
	s_cselect_b32 s37, s37, 0
	v_add_u32_e32 v168, s37, v165
	v_add_u32_e32 v169, s37, v164
	v_mfma_f32_16x16x32_f16 v[68:71], v[148:151], v[238:241], v[68:71]
	ds_read_b128 v[132:135], v168 offset:16
	ds_read_b128 v[184:187], v169 offset:16
	v_mfma_f32_16x16x32_f16 v[72:75], v[152:155], v[238:241], v[72:75]
	ds_read_b128 v[136:139], v168 offset:1040
	ds_read_b128 v[188:191], v169 offset:1040
	v_mfma_f32_16x16x32_f16 v[76:79], v[156:159], v[238:241], v[76:79]
	ds_read_b128 v[140:143], v168 offset:2064
	ds_read_b128 v[192:195], v169 offset:2064
	v_mfma_f32_16x16x32_f16 v[80:83], v[160:163], v[238:241], v[80:83]
	ds_read_b128 v[144:147], v168 offset:3088
	ds_read_b128 v[196:199], v169 offset:3088
	v_mfma_f32_16x16x32_f16 v[84:87], v[148:151], v[242:245], v[84:87]
	v_mfma_f32_16x16x32_f16 v[88:91], v[152:155], v[242:245], v[88:91]
	v_mfma_f32_16x16x32_f16 v[92:95], v[156:159], v[242:245], v[92:95]
	v_mfma_f32_16x16x32_f16 v[96:99], v[160:163], v[242:245], v[96:99]
	v_mfma_f32_16x16x32_f16 v[100:103], v[148:151], v[246:249], v[100:103]
	v_mfma_f32_16x16x32_f16 v[104:107], v[152:155], v[246:249], v[104:107]
	v_mfma_f32_16x16x32_f16 v[108:111], v[156:159], v[246:249], v[108:111]
	v_mfma_f32_16x16x32_f16 v[112:115], v[160:163], v[246:249], v[112:115]
	v_mfma_f32_16x16x32_f16 v[116:119], v[148:151], v[250:253], v[116:119]
	v_mfma_f32_16x16x32_f16 v[120:123], v[152:155], v[250:253], v[120:123]
	v_mfma_f32_16x16x32_f16 v[124:127], v[156:159], v[250:253], v[124:127]
	v_mfma_f32_16x16x32_f16 v[128:131], v[160:163], v[250:253], v[128:131]
	s_waitcnt lgkmcnt(0)
	s_mov_b32 s32, s37
	v_add_u32_e32 v169, s32, v164
	v_mfma_f32_16x16x32_f16 v[4:7], v[132:135], v[184:187], v[4:7]
	ds_read_b128 v[238:241], v169 offset:4112
	v_mfma_f32_16x16x32_f16 v[8:11], v[136:139], v[184:187], v[8:11]
	ds_read_b128 v[242:245], v169 offset:5136
	v_mfma_f32_16x16x32_f16 v[12:15], v[140:143], v[184:187], v[12:15]
	ds_read_b128 v[246:249], v169 offset:6160
	v_mfma_f32_16x16x32_f16 v[16:19], v[144:147], v[184:187], v[16:19]
	ds_read_b128 v[250:253], v169 offset:7184
	v_mfma_f32_16x16x32_f16 v[20:23], v[132:135], v[188:191], v[20:23]
	v_mfma_f32_16x16x32_f16 v[24:27], v[136:139], v[188:191], v[24:27]
	v_mfma_f32_16x16x32_f16 v[28:31], v[140:143], v[188:191], v[28:31]
	v_mfma_f32_16x16x32_f16 v[32:35], v[144:147], v[188:191], v[32:35]
	v_mfma_f32_16x16x32_f16 v[36:39], v[132:135], v[192:195], v[36:39]
	v_mfma_f32_16x16x32_f16 v[40:43], v[136:139], v[192:195], v[40:43]
	v_mfma_f32_16x16x32_f16 v[44:47], v[140:143], v[192:195], v[44:47]
	v_mfma_f32_16x16x32_f16 v[48:51], v[144:147], v[192:195], v[48:51]
	v_mfma_f32_16x16x32_f16 v[52:55], v[132:135], v[196:199], v[52:55]
	v_mfma_f32_16x16x32_f16 v[56:59], v[136:139], v[196:199], v[56:59]
	v_mfma_f32_16x16x32_f16 v[60:63], v[140:143], v[196:199], v[60:63]
	v_mfma_f32_16x16x32_f16 v[64:67], v[144:147], v[196:199], v[64:67]
	s_waitcnt vmcnt(0) lgkmcnt(0)
	s_barrier
	s_add_i32 s37, s32, 0x8000
	s_cmp_lg_u32 s32, 0x18000
	s_cselect_b32 s37, s37, 0
	v_add_u32_e32 v168, s37, v165
	v_add_u32_e32 v169, s37, v164
	v_mfma_f32_16x16x32_f16 v[68:71], v[132:135], v[238:241], v[68:71]
	ds_read_b128 v[148:151], v168 offset:16
	ds_read_b128 v[184:187], v169 offset:16
	v_mfma_f32_16x16x32_f16 v[72:75], v[136:139], v[238:241], v[72:75]
	ds_read_b128 v[152:155], v168 offset:1040
	ds_read_b128 v[188:191], v169 offset:1040
	v_mfma_f32_16x16x32_f16 v[76:79], v[140:143], v[238:241], v[76:79]
	ds_read_b128 v[156:159], v168 offset:2064
	ds_read_b128 v[192:195], v169 offset:2064
	v_mfma_f32_16x16x32_f16 v[80:83], v[144:147], v[238:241], v[80:83]
	ds_read_b128 v[160:163], v168 offset:3088
	ds_read_b128 v[196:199], v169 offset:3088
	v_mfma_f32_16x16x32_f16 v[84:87], v[132:135], v[242:245], v[84:87]
	v_mfma_f32_16x16x32_f16 v[88:91], v[136:139], v[242:245], v[88:91]
	v_mfma_f32_16x16x32_f16 v[92:95], v[140:143], v[242:245], v[92:95]
	v_mfma_f32_16x16x32_f16 v[96:99], v[144:147], v[242:245], v[96:99]
	v_mfma_f32_16x16x32_f16 v[100:103], v[132:135], v[246:249], v[100:103]
	v_mfma_f32_16x16x32_f16 v[104:107], v[136:139], v[246:249], v[104:107]
	v_mfma_f32_16x16x32_f16 v[108:111], v[140:143], v[246:249], v[108:111]
	v_mfma_f32_16x16x32_f16 v[112:115], v[144:147], v[246:249], v[112:115]
	v_mfma_f32_16x16x32_f16 v[116:119], v[132:135], v[250:253], v[116:119]
	v_mfma_f32_16x16x32_f16 v[120:123], v[136:139], v[250:253], v[120:123]
	v_mfma_f32_16x16x32_f16 v[124:127], v[140:143], v[250:253], v[124:127]
	v_mfma_f32_16x16x32_f16 v[128:131], v[144:147], v[250:253], v[128:131]
	s_waitcnt lgkmcnt(0)
	s_mov_b32 s32, s37
	v_add_u32_e32 v169, s32, v164
	v_mfma_f32_16x16x32_f16 v[4:7], v[148:151], v[184:187], v[4:7]
	ds_read_b128 v[238:241], v169 offset:4112
	v_mfma_f32_16x16x32_f16 v[8:11], v[152:155], v[184:187], v[8:11]
	ds_read_b128 v[242:245], v169 offset:5136
	v_mfma_f32_16x16x32_f16 v[12:15], v[156:159], v[184:187], v[12:15]
	ds_read_b128 v[246:249], v169 offset:6160
	v_mfma_f32_16x16x32_f16 v[16:19], v[160:163], v[184:187], v[16:19]
	ds_read_b128 v[250:253], v169 offset:7184
	v_mfma_f32_16x16x32_f16 v[20:23], v[148:151], v[188:191], v[20:23]
	v_mfma_f32_16x16x32_f16 v[24:27], v[152:155], v[188:191], v[24:27]
	v_mfma_f32_16x16x32_f16 v[28:31], v[156:159], v[188:191], v[28:31]
	v_mfma_f32_16x16x32_f16 v[32:35], v[160:163], v[188:191], v[32:35]
	v_mfma_f32_16x16x32_f16 v[36:39], v[148:151], v[192:195], v[36:39]
	v_mfma_f32_16x16x32_f16 v[40:43], v[152:155], v[192:195], v[40:43]
	v_mfma_f32_16x16x32_f16 v[44:47], v[156:159], v[192:195], v[44:47]
	v_mfma_f32_16x16x32_f16 v[48:51], v[160:163], v[192:195], v[48:51]
	v_mfma_f32_16x16x32_f16 v[52:55], v[148:151], v[196:199], v[52:55]
	v_mfma_f32_16x16x32_f16 v[56:59], v[152:155], v[196:199], v[56:59]
	v_mfma_f32_16x16x32_f16 v[60:63], v[156:159], v[196:199], v[60:63]
	v_mfma_f32_16x16x32_f16 v[64:67], v[160:163], v[196:199], v[64:67]
	s_waitcnt lgkmcnt(0)
	s_barrier
	v_mfma_f32_16x16x32_f16 v[68:71], v[148:151], v[238:241], v[68:71]
	v_mfma_f32_16x16x32_f16 v[72:75], v[152:155], v[238:241], v[72:75]
	v_mfma_f32_16x16x32_f16 v[76:79], v[156:159], v[238:241], v[76:79]
	v_mfma_f32_16x16x32_f16 v[80:83], v[160:163], v[238:241], v[80:83]
	v_mfma_f32_16x16x32_f16 v[84:87], v[148:151], v[242:245], v[84:87]
	v_mfma_f32_16x16x32_f16 v[88:91], v[152:155], v[242:245], v[88:91]
	v_mfma_f32_16x16x32_f16 v[92:95], v[156:159], v[242:245], v[92:95]
	v_mfma_f32_16x16x32_f16 v[96:99], v[160:163], v[242:245], v[96:99]
	v_mfma_f32_16x16x32_f16 v[100:103], v[148:151], v[246:249], v[100:103]
	v_mfma_f32_16x16x32_f16 v[104:107], v[152:155], v[246:249], v[104:107]
	v_mfma_f32_16x16x32_f16 v[108:111], v[156:159], v[246:249], v[108:111]
	v_mfma_f32_16x16x32_f16 v[112:115], v[160:163], v[246:249], v[112:115]
	v_mfma_f32_16x16x32_f16 v[116:119], v[148:151], v[250:253], v[116:119]
	v_mfma_f32_16x16x32_f16 v[120:123], v[152:155], v[250:253], v[120:123]
	v_mfma_f32_16x16x32_f16 v[124:127], v[156:159], v[250:253], v[124:127]
	v_mfma_f32_16x16x32_f16 v[128:131], v[160:163], v[250:253], v[128:131]
	s_lshl_b64 s[80:81], s[28:29], 13
	s_add_u32 s80, s80, s34
	s_addc_u32 s81, s81, s35
	s_lshl_b32 s82, s65, 1
	s_add_u32 s80, s80, s82
	s_addc_u32 s81, s81, 0
	v_and_b32_e32 v172, 15, v200
	v_bfe_u32 v173, v200, 4, 2
	v_bfe_u32 v174, v200, 6, 2
	v_bfe_u32 v175, v200, 8, 1
	v_lshl_or_b32 v175, v175, 7, v172
	v_lshlrev_b32_e32 v175, 13, v175
	v_lshlrev_b32_e32 v174, 6, v174
	v_lshl_or_b32 v174, v173, 2, v174
	v_lshl_add_u32 v177, v174, 1, v175
	v_max_f32_e32 v4, 0, v4
	v_max_f32_e32 v5, 0, v5
	v_max_f32_e32 v6, 0, v6
	v_max_f32_e32 v7, 0, v7
	v_pk_mul_f32 v[4:5], v[4:5], v[4:5]
	v_pk_mul_f32 v[6:7], v[6:7], v[6:7]
	v_cvt_pk_f16_f32 v172, v4, v5
	v_cvt_pk_f16_f32 v173, v6, v7
	global_store_dwordx2 v177, v[172:173], s[80:81]
	v_max_f32_e32 v8, 0, v8
	v_max_f32_e32 v9, 0, v9
	v_max_f32_e32 v10, 0, v10
	v_max_f32_e32 v11, 0, v11
	v_pk_mul_f32 v[8:9], v[8:9], v[8:9]
	v_pk_mul_f32 v[10:11], v[10:11], v[10:11]
	v_cvt_pk_f16_f32 v174, v8, v9
	v_cvt_pk_f16_f32 v175, v10, v11
	global_store_dwordx2 v177, v[174:175], s[80:81] offset:32
	v_max_f32_e32 v12, 0, v12
	v_max_f32_e32 v13, 0, v13
	v_max_f32_e32 v14, 0, v14
	v_max_f32_e32 v15, 0, v15
	v_pk_mul_f32 v[12:13], v[12:13], v[12:13]
	v_pk_mul_f32 v[14:15], v[14:15], v[14:15]
	v_cvt_pk_f16_f32 v172, v12, v13
	v_cvt_pk_f16_f32 v173, v14, v15
	global_store_dwordx2 v177, v[172:173], s[80:81] offset:64
	v_max_f32_e32 v16, 0, v16
	v_max_f32_e32 v17, 0, v17
	v_max_f32_e32 v18, 0, v18
	v_max_f32_e32 v19, 0, v19
	v_pk_mul_f32 v[16:17], v[16:17], v[16:17]
	v_pk_mul_f32 v[18:19], v[18:19], v[18:19]
	v_cvt_pk_f16_f32 v174, v16, v17
	v_cvt_pk_f16_f32 v175, v18, v19
	global_store_dwordx2 v177, v[174:175], s[80:81] offset:96
	v_add_u32_e32 v177, 0x20000, v177
	v_max_f32_e32 v20, 0, v20
	v_max_f32_e32 v21, 0, v21
	v_max_f32_e32 v22, 0, v22
	v_max_f32_e32 v23, 0, v23
	v_pk_mul_f32 v[20:21], v[20:21], v[20:21]
	v_pk_mul_f32 v[22:23], v[22:23], v[22:23]
	v_cvt_pk_f16_f32 v172, v20, v21
	v_cvt_pk_f16_f32 v173, v22, v23
	global_store_dwordx2 v177, v[172:173], s[80:81]
	v_max_f32_e32 v24, 0, v24
	v_max_f32_e32 v25, 0, v25
	v_max_f32_e32 v26, 0, v26
	v_max_f32_e32 v27, 0, v27
	v_pk_mul_f32 v[24:25], v[24:25], v[24:25]
	v_pk_mul_f32 v[26:27], v[26:27], v[26:27]
	v_cvt_pk_f16_f32 v174, v24, v25
	v_cvt_pk_f16_f32 v175, v26, v27
	global_store_dwordx2 v177, v[174:175], s[80:81] offset:32
	v_max_f32_e32 v28, 0, v28
	v_max_f32_e32 v29, 0, v29
	v_max_f32_e32 v30, 0, v30
	v_max_f32_e32 v31, 0, v31
	v_pk_mul_f32 v[28:29], v[28:29], v[28:29]
	v_pk_mul_f32 v[30:31], v[30:31], v[30:31]
	v_cvt_pk_f16_f32 v172, v28, v29
	v_cvt_pk_f16_f32 v173, v30, v31
	global_store_dwordx2 v177, v[172:173], s[80:81] offset:64
	v_max_f32_e32 v32, 0, v32
	v_max_f32_e32 v33, 0, v33
	v_max_f32_e32 v34, 0, v34
	v_max_f32_e32 v35, 0, v35
	v_pk_mul_f32 v[32:33], v[32:33], v[32:33]
	v_pk_mul_f32 v[34:35], v[34:35], v[34:35]
	v_cvt_pk_f16_f32 v174, v32, v33
	v_cvt_pk_f16_f32 v175, v34, v35
	global_store_dwordx2 v177, v[174:175], s[80:81] offset:96
	v_add_u32_e32 v177, 0x20000, v177
	v_max_f32_e32 v36, 0, v36
	v_max_f32_e32 v37, 0, v37
	v_max_f32_e32 v38, 0, v38
	v_max_f32_e32 v39, 0, v39
	v_pk_mul_f32 v[36:37], v[36:37], v[36:37]
	v_pk_mul_f32 v[38:39], v[38:39], v[38:39]
	v_cvt_pk_f16_f32 v172, v36, v37
	v_cvt_pk_f16_f32 v173, v38, v39
	global_store_dwordx2 v177, v[172:173], s[80:81]
	v_max_f32_e32 v40, 0, v40
	v_max_f32_e32 v41, 0, v41
	v_max_f32_e32 v42, 0, v42
	v_max_f32_e32 v43, 0, v43
	v_pk_mul_f32 v[40:41], v[40:41], v[40:41]
	v_pk_mul_f32 v[42:43], v[42:43], v[42:43]
	v_cvt_pk_f16_f32 v174, v40, v41
	v_cvt_pk_f16_f32 v175, v42, v43
	global_store_dwordx2 v177, v[174:175], s[80:81] offset:32
	v_max_f32_e32 v44, 0, v44
	v_max_f32_e32 v45, 0, v45
	v_max_f32_e32 v46, 0, v46
	v_max_f32_e32 v47, 0, v47
	v_pk_mul_f32 v[44:45], v[44:45], v[44:45]
	v_pk_mul_f32 v[46:47], v[46:47], v[46:47]
	v_cvt_pk_f16_f32 v172, v44, v45
	v_cvt_pk_f16_f32 v173, v46, v47
	global_store_dwordx2 v177, v[172:173], s[80:81] offset:64
	v_max_f32_e32 v48, 0, v48
	v_max_f32_e32 v49, 0, v49
	v_max_f32_e32 v50, 0, v50
	v_max_f32_e32 v51, 0, v51
	v_pk_mul_f32 v[48:49], v[48:49], v[48:49]
	v_pk_mul_f32 v[50:51], v[50:51], v[50:51]
	v_cvt_pk_f16_f32 v174, v48, v49
	v_cvt_pk_f16_f32 v175, v50, v51
	global_store_dwordx2 v177, v[174:175], s[80:81] offset:96
	v_add_u32_e32 v177, 0x20000, v177
	v_max_f32_e32 v52, 0, v52
	v_max_f32_e32 v53, 0, v53
	v_max_f32_e32 v54, 0, v54
	v_max_f32_e32 v55, 0, v55
	v_pk_mul_f32 v[52:53], v[52:53], v[52:53]
	v_pk_mul_f32 v[54:55], v[54:55], v[54:55]
	v_cvt_pk_f16_f32 v172, v52, v53
	v_cvt_pk_f16_f32 v173, v54, v55
	global_store_dwordx2 v177, v[172:173], s[80:81]
	v_max_f32_e32 v56, 0, v56
	v_max_f32_e32 v57, 0, v57
	v_max_f32_e32 v58, 0, v58
	v_max_f32_e32 v59, 0, v59
	v_pk_mul_f32 v[56:57], v[56:57], v[56:57]
	v_pk_mul_f32 v[58:59], v[58:59], v[58:59]
	v_cvt_pk_f16_f32 v174, v56, v57
	v_cvt_pk_f16_f32 v175, v58, v59
	global_store_dwordx2 v177, v[174:175], s[80:81] offset:32
	v_max_f32_e32 v60, 0, v60
	v_max_f32_e32 v61, 0, v61
	v_max_f32_e32 v62, 0, v62
	v_max_f32_e32 v63, 0, v63
	v_pk_mul_f32 v[60:61], v[60:61], v[60:61]
	v_pk_mul_f32 v[62:63], v[62:63], v[62:63]
	v_cvt_pk_f16_f32 v172, v60, v61
	v_cvt_pk_f16_f32 v173, v62, v63
	global_store_dwordx2 v177, v[172:173], s[80:81] offset:64
	v_max_f32_e32 v64, 0, v64
	v_max_f32_e32 v65, 0, v65
	v_max_f32_e32 v66, 0, v66
	v_max_f32_e32 v67, 0, v67
	v_pk_mul_f32 v[64:65], v[64:65], v[64:65]
	v_pk_mul_f32 v[66:67], v[66:67], v[66:67]
	v_cvt_pk_f16_f32 v174, v64, v65
	v_cvt_pk_f16_f32 v175, v66, v67
	global_store_dwordx2 v177, v[174:175], s[80:81] offset:96
	v_add_u32_e32 v177, 0x20000, v177
	v_max_f32_e32 v68, 0, v68
	v_max_f32_e32 v69, 0, v69
	v_max_f32_e32 v70, 0, v70
	v_max_f32_e32 v71, 0, v71
	v_pk_mul_f32 v[68:69], v[68:69], v[68:69]
	v_pk_mul_f32 v[70:71], v[70:71], v[70:71]
	v_cvt_pk_f16_f32 v172, v68, v69
	v_cvt_pk_f16_f32 v173, v70, v71
	global_store_dwordx2 v177, v[172:173], s[80:81]
	v_max_f32_e32 v72, 0, v72
	v_max_f32_e32 v73, 0, v73
	v_max_f32_e32 v74, 0, v74
	v_max_f32_e32 v75, 0, v75
	v_pk_mul_f32 v[72:73], v[72:73], v[72:73]
	v_pk_mul_f32 v[74:75], v[74:75], v[74:75]
	v_cvt_pk_f16_f32 v174, v72, v73
	v_cvt_pk_f16_f32 v175, v74, v75
	global_store_dwordx2 v177, v[174:175], s[80:81] offset:32
	v_max_f32_e32 v76, 0, v76
	v_max_f32_e32 v77, 0, v77
	v_max_f32_e32 v78, 0, v78
	v_max_f32_e32 v79, 0, v79
	v_pk_mul_f32 v[76:77], v[76:77], v[76:77]
	v_pk_mul_f32 v[78:79], v[78:79], v[78:79]
	v_cvt_pk_f16_f32 v172, v76, v77
	v_cvt_pk_f16_f32 v173, v78, v79
	global_store_dwordx2 v177, v[172:173], s[80:81] offset:64
	v_max_f32_e32 v80, 0, v80
	v_max_f32_e32 v81, 0, v81
	v_max_f32_e32 v82, 0, v82
	v_max_f32_e32 v83, 0, v83
	v_pk_mul_f32 v[80:81], v[80:81], v[80:81]
	v_pk_mul_f32 v[82:83], v[82:83], v[82:83]
	v_cvt_pk_f16_f32 v174, v80, v81
	v_cvt_pk_f16_f32 v175, v82, v83
	global_store_dwordx2 v177, v[174:175], s[80:81] offset:96
	v_add_u32_e32 v177, 0x20000, v177
	v_max_f32_e32 v84, 0, v84
	v_max_f32_e32 v85, 0, v85
	v_max_f32_e32 v86, 0, v86
	v_max_f32_e32 v87, 0, v87
	v_pk_mul_f32 v[84:85], v[84:85], v[84:85]
	v_pk_mul_f32 v[86:87], v[86:87], v[86:87]
	v_cvt_pk_f16_f32 v172, v84, v85
	v_cvt_pk_f16_f32 v173, v86, v87
	global_store_dwordx2 v177, v[172:173], s[80:81]
	v_max_f32_e32 v88, 0, v88
	v_max_f32_e32 v89, 0, v89
	v_max_f32_e32 v90, 0, v90
	v_max_f32_e32 v91, 0, v91
	v_pk_mul_f32 v[88:89], v[88:89], v[88:89]
	v_pk_mul_f32 v[90:91], v[90:91], v[90:91]
	v_cvt_pk_f16_f32 v174, v88, v89
	v_cvt_pk_f16_f32 v175, v90, v91
	global_store_dwordx2 v177, v[174:175], s[80:81] offset:32
	v_max_f32_e32 v92, 0, v92
	v_max_f32_e32 v93, 0, v93
	v_max_f32_e32 v94, 0, v94
	v_max_f32_e32 v95, 0, v95
	v_pk_mul_f32 v[92:93], v[92:93], v[92:93]
	v_pk_mul_f32 v[94:95], v[94:95], v[94:95]
	v_cvt_pk_f16_f32 v172, v92, v93
	v_cvt_pk_f16_f32 v173, v94, v95
	global_store_dwordx2 v177, v[172:173], s[80:81] offset:64
	v_max_f32_e32 v96, 0, v96
	v_max_f32_e32 v97, 0, v97
	v_max_f32_e32 v98, 0, v98
	v_max_f32_e32 v99, 0, v99
	v_pk_mul_f32 v[96:97], v[96:97], v[96:97]
	v_pk_mul_f32 v[98:99], v[98:99], v[98:99]
	v_cvt_pk_f16_f32 v174, v96, v97
	v_cvt_pk_f16_f32 v175, v98, v99
	global_store_dwordx2 v177, v[174:175], s[80:81] offset:96
	v_add_u32_e32 v177, 0x20000, v177
	v_max_f32_e32 v100, 0, v100
	v_max_f32_e32 v101, 0, v101
	v_max_f32_e32 v102, 0, v102
	v_max_f32_e32 v103, 0, v103
	v_pk_mul_f32 v[100:101], v[100:101], v[100:101]
	v_pk_mul_f32 v[102:103], v[102:103], v[102:103]
	v_cvt_pk_f16_f32 v172, v100, v101
	v_cvt_pk_f16_f32 v173, v102, v103
	global_store_dwordx2 v177, v[172:173], s[80:81]
	v_max_f32_e32 v104, 0, v104
	v_max_f32_e32 v105, 0, v105
	v_max_f32_e32 v106, 0, v106
	v_max_f32_e32 v107, 0, v107
	v_pk_mul_f32 v[104:105], v[104:105], v[104:105]
	v_pk_mul_f32 v[106:107], v[106:107], v[106:107]
	v_cvt_pk_f16_f32 v174, v104, v105
	v_cvt_pk_f16_f32 v175, v106, v107
	global_store_dwordx2 v177, v[174:175], s[80:81] offset:32
	v_max_f32_e32 v108, 0, v108
	v_max_f32_e32 v109, 0, v109
	v_max_f32_e32 v110, 0, v110
	v_max_f32_e32 v111, 0, v111
	v_pk_mul_f32 v[108:109], v[108:109], v[108:109]
	v_pk_mul_f32 v[110:111], v[110:111], v[110:111]
	v_cvt_pk_f16_f32 v172, v108, v109
	v_cvt_pk_f16_f32 v173, v110, v111
	global_store_dwordx2 v177, v[172:173], s[80:81] offset:64
	v_max_f32_e32 v112, 0, v112
	v_max_f32_e32 v113, 0, v113
	v_max_f32_e32 v114, 0, v114
	v_max_f32_e32 v115, 0, v115
	v_pk_mul_f32 v[112:113], v[112:113], v[112:113]
	v_pk_mul_f32 v[114:115], v[114:115], v[114:115]
	v_cvt_pk_f16_f32 v174, v112, v113
	v_cvt_pk_f16_f32 v175, v114, v115
	global_store_dwordx2 v177, v[174:175], s[80:81] offset:96
	v_add_u32_e32 v177, 0x20000, v177
	v_max_f32_e32 v116, 0, v116
	v_max_f32_e32 v117, 0, v117
	v_max_f32_e32 v118, 0, v118
	v_max_f32_e32 v119, 0, v119
	v_pk_mul_f32 v[116:117], v[116:117], v[116:117]
	v_pk_mul_f32 v[118:119], v[118:119], v[118:119]
	v_cvt_pk_f16_f32 v172, v116, v117
	v_cvt_pk_f16_f32 v173, v118, v119
	global_store_dwordx2 v177, v[172:173], s[80:81]
	v_max_f32_e32 v120, 0, v120
	v_max_f32_e32 v121, 0, v121
	v_max_f32_e32 v122, 0, v122
	v_max_f32_e32 v123, 0, v123
	v_pk_mul_f32 v[120:121], v[120:121], v[120:121]
	v_pk_mul_f32 v[122:123], v[122:123], v[122:123]
	v_cvt_pk_f16_f32 v174, v120, v121
	v_cvt_pk_f16_f32 v175, v122, v123
	global_store_dwordx2 v177, v[174:175], s[80:81] offset:32
	v_max_f32_e32 v124, 0, v124
	v_max_f32_e32 v125, 0, v125
	v_max_f32_e32 v126, 0, v126
	v_max_f32_e32 v127, 0, v127
	v_pk_mul_f32 v[124:125], v[124:125], v[124:125]
	v_pk_mul_f32 v[126:127], v[126:127], v[126:127]
	v_cvt_pk_f16_f32 v172, v124, v125
	v_cvt_pk_f16_f32 v173, v126, v127
	global_store_dwordx2 v177, v[172:173], s[80:81] offset:64
	v_max_f32_e32 v128, 0, v128
	v_max_f32_e32 v129, 0, v129
	v_max_f32_e32 v130, 0, v130
	v_max_f32_e32 v131, 0, v131
	v_pk_mul_f32 v[128:129], v[128:129], v[128:129]
	v_pk_mul_f32 v[130:131], v[130:131], v[130:131]
	v_cvt_pk_f16_f32 v174, v128, v129
	v_cvt_pk_f16_f32 v175, v130, v131
	global_store_dwordx2 v177, v[174:175], s[80:81] offset:96
	s_nop 1
	s_add_i32 s56, s56, s76
	s_cmp_ge_i32 s56, s58
	s_cbranch_scc1 .LBB0_127
	s_branch .LBB0_111
